# norm phases: output rows stored with the nt (streaming) cache hint
# speedup vs baseline: 1.0008x; 1.0008x over previous
.LBB0_180:
	s_or_b64 exec, exec, s[18:19]
	v_lshlrev_b32_e32 v80, 16, v6
	v_and_b32_e32 v81, 0xffff0000, v6
	v_lshlrev_b32_e32 v76, 16, v7
	v_and_b32_e32 v77, 0xffff0000, v7
	v_pk_mul_f32 v[6:7], v[80:81], v[80:81]
	v_pk_mul_f32 v[78:79], v[76:77], v[76:77]
	v_add_f32_e32 v6, v6, v7
	v_lshlrev_b32_e32 v74, 16, v8
	v_and_b32_e32 v75, 0xffff0000, v8
	v_add_f32_e32 v6, v78, v6
	v_lshlrev_b32_e32 v70, 16, v9
	v_and_b32_e32 v71, 0xffff0000, v9
	v_pk_mul_f32 v[8:9], v[74:75], v[74:75]
	v_add_f32_e32 v6, v79, v6
	v_add_f32_e32 v6, v8, v6
	v_pk_mul_f32 v[72:73], v[70:71], v[70:71]
	v_add_f32_e32 v6, v9, v6
	v_lshlrev_b32_e32 v92, 16, v2
	v_and_b32_e32 v93, 0xffff0000, v2
	v_add_f32_e32 v6, v72, v6
	v_lshlrev_b32_e32 v88, 16, v3
	v_and_b32_e32 v89, 0xffff0000, v3
	v_pk_mul_f32 v[2:3], v[92:93], v[92:93]
	v_add_f32_e32 v6, v73, v6
	v_add_f32_e32 v2, v2, v6
	v_pk_mul_f32 v[90:91], v[88:89], v[88:89]
	v_add_f32_e32 v2, v3, v2
	v_lshlrev_b32_e32 v86, 16, v4
	v_and_b32_e32 v87, 0xffff0000, v4
	v_add_f32_e32 v2, v90, v2
	v_lshlrev_b32_e32 v82, 16, v5
	v_and_b32_e32 v83, 0xffff0000, v5
	v_pk_mul_f32 v[4:5], v[86:87], v[86:87]
	v_add_f32_e32 v2, v91, v2
	v_add_f32_e32 v2, v4, v2
	v_pk_mul_f32 v[84:85], v[82:83], v[82:83]
	v_add_f32_e32 v2, v5, v2
	v_add_f32_e32 v2, v84, v2
	v_add_f32_e32 v2, v85, v2
	ds_bpermute_b32 v3, v64, v2
	s_and_b64 s[4:5], exec, s[4:5]
	v_lshl_add_u64 v[6:7], v[38:39], 0, v[36:37]
	s_or_b64 s[14:15], s[4:5], s[14:15]
	s_mov_b32 s4, 0x15200000
	s_waitcnt lgkmcnt(0)
	v_add_f32_e32 v2, v2, v3
	ds_bpermute_b32 v3, v65, v2
	v_mov_b32_e32 v62, v63
	s_waitcnt lgkmcnt(0)
	v_add_f32_e32 v2, v2, v3
	ds_bpermute_b32 v3, v66, v2
	s_waitcnt lgkmcnt(0)
	v_add_f32_e32 v2, v2, v3
	ds_bpermute_b32 v3, v67, v2
	s_waitcnt lgkmcnt(0)
	v_add_f32_e32 v2, v2, v3
	ds_bpermute_b32 v3, v68, v2
	s_waitcnt lgkmcnt(0)
	v_add_f32_e32 v2, v2, v3
	ds_bpermute_b32 v3, v69, v2
	s_waitcnt lgkmcnt(0)
	v_add_f32_e32 v2, v2, v3
	v_fmamk_f32 v2, v2, 0x3a800000, v179
	v_mul_f32_e32 v3, 0x4b800000, v2
	v_cmp_gt_f32_e32 vcc, s71, v2
	s_nop 1
	v_cndmask_b32_e32 v2, v2, v3, vcc
	v_rsq_f32_e32 v2, v2
	s_nop 0
	v_mul_f32_e32 v3, 0x45800000, v2
	v_cndmask_b32_e32 v8, v2, v3, vcc
	v_pk_mul_f32 v[2:3], v[8:9], v[80:81] op_sel_hi:[0,1]
	v_pk_mul_f32 v[4:5], v[8:9], v[76:77] op_sel_hi:[0,1]
	v_pk_mul_f32 v[72:73], v[8:9], v[74:75] op_sel_hi:[0,1]
	v_pk_mul_f32 v[70:71], v[8:9], v[70:71] op_sel_hi:[0,1]
	s_waitcnt vmcnt(3)
	v_pk_fma_f32 v[2:3], v[58:59], v[2:3], v[22:23]
	v_pk_fma_f32 v[4:5], v[56:57], v[4:5], v[24:25]
	s_waitcnt vmcnt(2)
	v_pk_fma_f32 v[72:73], v[54:55], v[72:73], v[10:11]
	v_pk_fma_f32 v[70:71], v[52:53], v[70:71], v[12:13]
	v_add_co_u32_e32 v6, vcc, s4, v6
	v_cvt_pk_bf16_f32 v2, v2, v3
	v_cvt_pk_bf16_f32 v3, v4, v5
	v_cvt_pk_bf16_f32 v4, v72, v73
	v_cvt_pk_bf16_f32 v5, v70, v71
	v_addc_co_u32_e32 v7, vcc, 0, v7, vcc
	global_store_dwordx4 v[6:7], v[2:5], off nt
	v_pk_mul_f32 v[70:71], v[8:9], v[86:87] op_sel_hi:[0,1]
	s_waitcnt vmcnt(1)
	v_pk_fma_f32 v[70:71], v[46:47], v[70:71], v[30:31]
	v_pk_mul_f32 v[2:3], v[8:9], v[92:93] op_sel_hi:[0,1]
	v_pk_mul_f32 v[4:5], v[8:9], v[88:89] op_sel_hi:[0,1]
	v_pk_mul_f32 v[8:9], v[8:9], v[82:83] op_sel_hi:[0,1]
	v_pk_fma_f32 v[2:3], v[50:51], v[2:3], v[26:27]
	v_pk_fma_f32 v[4:5], v[48:49], v[4:5], v[28:29]
	v_pk_fma_f32 v[8:9], v[60:61], v[8:9], v[32:33]
	v_cvt_pk_bf16_f32 v2, v2, v3
	v_cvt_pk_bf16_f32 v3, v4, v5
	v_cvt_pk_bf16_f32 v4, v70, v71
	v_cvt_pk_bf16_f32 v5, v8, v9
	s_mov_b64 s[4:5], 0x800
	global_store_dwordx4 v[6:7], v[2:5], off offset:1024 nt
	v_lshl_add_u64 v[38:39], v[38:39], 0, s[4:5]
	s_mov_b64 s[4:5], 0x1000
	v_mov_b64_e32 v[6:7], v[18:19]
	v_mov_b64_e32 v[2:3], v[14:15]
	v_lshl_add_u64 v[34:35], v[34:35], 0, s[4:5]
	v_mov_b64_e32 v[8:9], v[20:21]
	v_mov_b64_e32 v[4:5], v[16:17]
	s_andn2_b64 exec, exec, s[14:15]
	s_cbranch_execz .LBB0_185

.LBB0_189:
	s_or_b64 exec, exec, s[2:3]
	v_pk_mul_f32 v[100:101], v[72:73], v[72:73]
	v_pk_mul_f32 v[102:103], v[68:69], v[68:69]
	v_pk_mul_f32 v[96:97], v[74:75], v[74:75]
	v_pk_mul_f32 v[98:99], v[70:71], v[70:71]
	v_mov_b32_e32 v104, v100
	v_mov_b32_e32 v105, v102
	v_mov_b32_e32 v102, v101
	v_pk_add_f32 v[100:101], v[104:105], v[102:103]
	v_mov_b32_e32 v102, v96
	v_mov_b32_e32 v103, v98
	v_pk_mul_f32 v[92:93], v[60:61], v[60:61]
	v_pk_mul_f32 v[94:95], v[64:65], v[64:65]
	v_pk_add_f32 v[100:101], v[102:103], v[100:101]
	v_mov_b32_e32 v98, v97
	v_pk_mul_f32 v[88:89], v[62:63], v[62:63]
	v_pk_mul_f32 v[90:91], v[66:67], v[66:67]
	v_pk_add_f32 v[96:97], v[98:99], v[100:101]
	v_mov_b32_e32 v98, v92
	v_mov_b32_e32 v99, v94
	v_mov_b32_e32 v94, v93
	v_pk_add_f32 v[92:93], v[98:99], v[94:95]
	v_mov_b32_e32 v94, v88
	v_mov_b32_e32 v95, v90
	v_pk_add_f32 v[92:93], v[94:95], v[92:93]
	v_mov_b32_e32 v90, v89
	v_pk_add_f32 v[88:89], v[90:91], v[92:93]
	v_add_f32_e32 v41, v96, v97
	v_add_f32_e32 v41, v89, v41
	v_add_f32_e32 v41, v88, v41
	ds_bpermute_b32 v43, v82, v41
	s_and_b64 s[2:3], exec, vcc
	s_or_b64 s[12:13], s[2:3], s[12:13]
	s_mov_b64 s[2:3], 0x800
	s_waitcnt lgkmcnt(0)
	v_add_f32_e32 v41, v41, v43
	ds_bpermute_b32 v43, v83, v41
	s_waitcnt lgkmcnt(0)
	v_add_f32_e32 v41, v41, v43
	ds_bpermute_b32 v43, v84, v41
	s_waitcnt lgkmcnt(0)
	v_add_f32_e32 v41, v41, v43
	ds_bpermute_b32 v43, v85, v41
	s_waitcnt lgkmcnt(0)
	v_add_f32_e32 v41, v41, v43
	ds_bpermute_b32 v43, v86, v41
	s_waitcnt lgkmcnt(0)
	v_add_f32_e32 v41, v41, v43
	ds_bpermute_b32 v43, v87, v41
	s_waitcnt lgkmcnt(0)
	v_add_f32_e32 v41, v41, v43
	v_fmamk_f32 v41, v41, 0x3a800000, v179
	v_mul_f32_e32 v43, 0x4b800000, v41
	v_cmp_gt_f32_e64 s[4:5], s71, v41
	s_nop 1
	v_cndmask_b32_e64 v41, v41, v43, s[4:5]
	v_rsq_f32_e32 v41, v41
	s_nop 0
	v_mul_f32_e32 v43, 0x45800000, v41
	v_cndmask_b32_e64 v80, v41, v43, s[4:5]
	v_pk_mul_f32 v[72:73], v[72:73], v[80:81] op_sel_hi:[1,0]
	v_pk_mul_f32 v[74:75], v[74:75], v[80:81] op_sel_hi:[1,0]
	v_pk_mul_f32 v[68:69], v[68:69], v[80:81] op_sel_hi:[1,0]
	v_pk_mul_f32 v[70:71], v[70:71], v[80:81] op_sel_hi:[1,0]
	v_pk_mul_f32 v[64:65], v[64:65], v[80:81] op_sel_hi:[1,0]
	v_pk_mul_f32 v[66:67], v[66:67], v[80:81] op_sel_hi:[1,0]
	v_pk_mul_f32 v[60:61], v[60:61], v[80:81] op_sel_hi:[1,0]
	v_pk_mul_f32 v[62:63], v[62:63], v[80:81] op_sel_hi:[1,0]
	v_pk_fma_f32 v[74:75], v[36:37], v[74:75], v[20:21]
	v_pk_fma_f32 v[72:73], v[34:35], v[72:73], v[18:19]
	v_pk_fma_f32 v[70:71], v[54:55], v[70:71], v[24:25]
	v_pk_fma_f32 v[68:69], v[52:53], v[68:69], v[22:23]
	v_pk_fma_f32 v[66:67], v[58:59], v[66:67], v[28:29]
	v_pk_fma_f32 v[64:65], v[56:57], v[64:65], v[26:27]
	s_waitcnt vmcnt(0)
	v_pk_fma_f32 v[62:63], v[78:79], v[62:63], v[32:33]
	v_pk_fma_f32 v[60:61], v[76:77], v[60:61], v[30:31]
	v_cvt_pk_bf16_f32 v72, v72, v73
	v_cvt_pk_bf16_f32 v73, v74, v75
	v_cvt_pk_bf16_f32 v68, v68, v69
	v_cvt_pk_bf16_f32 v69, v70, v71
	v_cvt_pk_bf16_f32 v64, v64, v65
	v_cvt_pk_bf16_f32 v65, v66, v67
	v_cvt_pk_bf16_f32 v60, v60, v61
	v_cvt_pk_bf16_f32 v61, v62, v63
	global_store_dwordx2 v[48:49], v[72:73], off nt
	global_store_dwordx2 v[48:49], v[68:69], off offset:512 nt
	global_store_dwordx2 v[48:49], v[64:65], off offset:1024 nt
	global_store_dwordx2 v[48:49], v[60:61], off offset:1536 nt
	v_lshl_add_u64 v[48:49], v[48:49], 0, s[2:3]
	s_mov_b64 s[2:3], 0x1000
	v_lshl_add_u64 v[50:51], v[50:51], 0, s[2:3]
	v_mov_b32_e32 v80, v81
	v_mov_b32_e32 v72, v2
	v_mov_b32_e32 v73, v3
	v_mov_b32_e32 v74, v4
	v_mov_b32_e32 v75, v5
	v_mov_b32_e32 v68, v6
	v_mov_b32_e32 v69, v7
	v_mov_b32_e32 v70, v8
	v_mov_b32_e32 v71, v9
	v_mov_b32_e32 v64, v10
	v_mov_b32_e32 v65, v11
	v_mov_b32_e32 v66, v12
	v_mov_b32_e32 v67, v13
	v_mov_b32_e32 v60, v14
	v_mov_b32_e32 v61, v15
	v_mov_b32_e32 v62, v16
	v_mov_b32_e32 v63, v17
	s_andn2_b64 exec, exec, s[12:13]
	s_cbranch_execz .LBB0_194

.LBB0_460:
	s_or_b64 exec, exec, s[10:11]
	v_lshlrev_b32_e32 v84, 16, v22
	v_and_b32_e32 v85, 0xffff0000, v22
	v_lshlrev_b32_e32 v80, 16, v23
	v_and_b32_e32 v81, 0xffff0000, v23
	v_pk_mul_f32 v[22:23], v[84:85], v[84:85]
	v_pk_mul_f32 v[82:83], v[80:81], v[80:81]
	v_add_f32_e32 v22, v22, v23
	v_lshlrev_b32_e32 v78, 16, v24
	v_and_b32_e32 v79, 0xffff0000, v24
	v_add_f32_e32 v22, v82, v22
	v_lshlrev_b32_e32 v74, 16, v25
	v_and_b32_e32 v75, 0xffff0000, v25
	v_pk_mul_f32 v[24:25], v[78:79], v[78:79]
	v_add_f32_e32 v22, v83, v22
	v_add_f32_e32 v22, v24, v22
	v_pk_mul_f32 v[76:77], v[74:75], v[74:75]
	v_add_f32_e32 v22, v25, v22
	v_lshlrev_b32_e32 v96, 16, v10
	v_and_b32_e32 v97, 0xffff0000, v10
	v_add_f32_e32 v22, v76, v22
	v_lshlrev_b32_e32 v92, 16, v11
	v_and_b32_e32 v93, 0xffff0000, v11
	v_pk_mul_f32 v[10:11], v[96:97], v[96:97]
	v_add_f32_e32 v22, v77, v22
	v_add_f32_e32 v10, v10, v22
	v_pk_mul_f32 v[94:95], v[92:93], v[92:93]
	v_add_f32_e32 v10, v11, v10
	v_lshlrev_b32_e32 v90, 16, v12
	v_and_b32_e32 v91, 0xffff0000, v12
	v_add_f32_e32 v10, v94, v10
	v_lshlrev_b32_e32 v86, 16, v13
	v_and_b32_e32 v87, 0xffff0000, v13
	v_pk_mul_f32 v[12:13], v[90:91], v[90:91]
	v_add_f32_e32 v10, v95, v10
	v_add_f32_e32 v10, v12, v10
	v_pk_mul_f32 v[88:89], v[86:87], v[86:87]
	v_add_f32_e32 v10, v13, v10
	v_add_f32_e32 v10, v88, v10
	v_add_f32_e32 v10, v89, v10
	ds_bpermute_b32 v11, v66, v10
	s_and_b64 s[4:5], exec, s[4:5]
	s_or_b64 s[8:9], s[4:5], s[8:9]
	v_lshl_add_u64 v[72:73], v[50:51], 0, v[36:37]
	s_mov_b32 s4, 0x15200000
	s_waitcnt lgkmcnt(0)
	v_add_f32_e32 v10, v10, v11
	ds_bpermute_b32 v11, v67, v10
	v_mov_b32_e32 v64, v65
	s_waitcnt lgkmcnt(0)
	v_add_f32_e32 v10, v10, v11
	ds_bpermute_b32 v11, v68, v10
	s_waitcnt lgkmcnt(0)
	v_add_f32_e32 v10, v10, v11
	ds_bpermute_b32 v11, v69, v10
	s_waitcnt lgkmcnt(0)
	v_add_f32_e32 v10, v10, v11
	ds_bpermute_b32 v11, v70, v10
	s_waitcnt lgkmcnt(0)
	v_add_f32_e32 v10, v10, v11
	ds_bpermute_b32 v11, v71, v10
	s_waitcnt lgkmcnt(0)
	v_add_f32_e32 v10, v10, v11
	v_fmamk_f32 v10, v10, 0x3a800000, v179
	v_cmp_gt_f32_e32 vcc, s71, v10
	v_mul_f32_e32 v11, 0x4b800000, v10
	s_nop 0
	v_cndmask_b32_e32 v10, v10, v11, vcc
	v_rsq_f32_e32 v10, v10
	s_nop 0
	v_mul_f32_e32 v11, 0x45800000, v10
	v_cndmask_b32_e32 v22, v10, v11, vcc
	v_pk_mul_f32 v[10:11], v[22:23], v[84:85] op_sel_hi:[0,1]
	v_pk_mul_f32 v[12:13], v[22:23], v[80:81] op_sel_hi:[0,1]
	v_pk_mul_f32 v[24:25], v[22:23], v[78:79] op_sel_hi:[0,1]
	v_pk_fma_f32 v[10:11], v[38:39], v[10:11], v[6:7]
	v_pk_fma_f32 v[12:13], v[40:41], v[12:13], v[8:9]
	v_pk_fma_f32 v[24:25], v[42:43], v[24:25], v[2:3]
	v_pk_mul_f32 v[74:75], v[22:23], v[74:75] op_sel_hi:[0,1]
	v_pk_fma_f32 v[74:75], v[44:45], v[74:75], v[4:5]
	v_cvt_pk_bf16_f32 v10, v10, v11
	v_cvt_pk_bf16_f32 v11, v12, v13
	v_cvt_pk_bf16_f32 v12, v24, v25
	v_add_co_u32_e32 v24, vcc, s4, v72
	v_cvt_pk_bf16_f32 v13, v74, v75
	s_nop 0
	v_addc_co_u32_e32 v25, vcc, 0, v73, vcc
	global_store_dwordx4 v[24:25], v[10:13], off nt
	v_pk_mul_f32 v[72:73], v[22:23], v[90:91] op_sel_hi:[0,1]
	s_waitcnt vmcnt(1)
	v_pk_fma_f32 v[72:73], v[60:61], v[72:73], v[30:31]
	v_pk_mul_f32 v[10:11], v[22:23], v[96:97] op_sel_hi:[0,1]
	v_pk_mul_f32 v[12:13], v[22:23], v[92:93] op_sel_hi:[0,1]
	v_pk_mul_f32 v[22:23], v[22:23], v[86:87] op_sel_hi:[0,1]
	v_pk_fma_f32 v[10:11], v[56:57], v[10:11], v[26:27]
	v_pk_fma_f32 v[12:13], v[58:59], v[12:13], v[28:29]
	v_pk_fma_f32 v[22:23], v[62:63], v[22:23], v[32:33]
	v_cvt_pk_bf16_f32 v10, v10, v11
	v_cvt_pk_bf16_f32 v11, v12, v13
	v_cvt_pk_bf16_f32 v12, v72, v73
	v_cvt_pk_bf16_f32 v13, v22, v23
	s_mov_b64 s[4:5], 0x800
	global_store_dwordx4 v[24:25], v[10:13], off offset:1024 nt
	v_lshl_add_u64 v[50:51], v[50:51], 0, s[4:5]
	s_mov_b64 s[4:5], 0x1000
	v_mov_b64_e32 v[24:25], v[20:21]
	v_mov_b64_e32 v[10:11], v[14:15]
	v_lshl_add_u64 v[34:35], v[34:35], 0, s[4:5]
	v_mov_b64_e32 v[22:23], v[18:19]
	v_mov_b64_e32 v[12:13], v[16:17]
	s_andn2_b64 exec, exec, s[8:9]
	s_cbranch_execz .LBB0_465
